# nt (non-temporal) hint on the final-norm d_out stores only
# speedup vs baseline: 1.0062x; 1.0062x over previous
.LBB0_2584:
	v_lshlrev_b32_e32 v48, 16, v36
	v_and_b32_e32 v49, 0xffff0000, v36
	v_lshlrev_b32_e32 v36, 16, v37
	v_and_b32_e32 v37, 0xffff0000, v37
	v_mul_f32_e32 v50, v49, v49
	v_mul_f32_e32 v51, v37, v37
	v_fmac_f32_e32 v50, v48, v48
	v_fmac_f32_e32 v51, v36, v36
	v_add_f32_e32 v52, v50, v51
	v_lshlrev_b32_e32 v50, 16, v34
	v_and_b32_e32 v51, 0xffff0000, v34
	v_lshlrev_b32_e32 v34, 16, v35
	v_and_b32_e32 v35, 0xffff0000, v35
	v_mul_f32_e32 v53, v51, v51
	v_mul_f32_e32 v54, v35, v35
	v_fmac_f32_e32 v53, v50, v50
	v_fmac_f32_e32 v54, v34, v34
	v_add_f32_e32 v53, v53, v54
	v_add_f32_e32 v56, v53, v52
	v_and_b32_e32 v53, 0xffff0000, v32
	v_and_b32_e32 v55, 0xffff0000, v33
	v_lshlrev_b32_e32 v52, 16, v32
	v_lshlrev_b32_e32 v54, 16, v33
	v_mul_f32_e32 v32, v53, v53
	v_mul_f32_e32 v33, v55, v55
	v_fmac_f32_e32 v32, v52, v52
	v_fmac_f32_e32 v33, v54, v54
	v_add_f32_e32 v32, v32, v33
	v_and_b32_e32 v57, 0xffff0000, v30
	v_and_b32_e32 v59, 0xffff0000, v31
	v_add_f32_e32 v32, v32, v56
	v_lshlrev_b32_e32 v56, 16, v30
	v_lshlrev_b32_e32 v58, 16, v31
	v_mul_f32_e32 v30, v57, v57
	v_mul_f32_e32 v31, v59, v59
	v_fmac_f32_e32 v30, v56, v56
	v_fmac_f32_e32 v31, v58, v58
	v_add_f32_e32 v30, v30, v31
	v_add_f32_e32 v30, v30, v32
	ds_swizzle_b32 v31, v30 offset:swizzle(SWAP,1)
	s_ashr_i32 s5, s4, 31
	s_lshl_b64 s[10:11], s[4:5], 12
	v_lshl_add_u64 v[62:63], v[18:19], 0, s[10:11]
	v_lshl_add_u64 v[20:21], v[20:21], 0, s[2:3]
	s_waitcnt lgkmcnt(0)
	v_add_f32_e32 v30, v30, v31
	ds_swizzle_b32 v31, v30 offset:swizzle(SWAP,2)
	s_add_i32 s4, s4, s16
	s_mov_b64 s[12:13], s[8:9]
	s_waitcnt lgkmcnt(0)
	v_add_f32_e32 v30, v30, v31
	ds_swizzle_b32 v31, v30 offset:swizzle(SWAP,4)
	s_waitcnt lgkmcnt(0)
	v_add_f32_e32 v30, v30, v31
	ds_swizzle_b32 v31, v30 offset:swizzle(SWAP,8)
	s_waitcnt lgkmcnt(0)
	v_add_f32_e32 v30, v30, v31
	ds_swizzle_b32 v31, v30 offset:swizzle(SWAP,16)
	s_waitcnt lgkmcnt(0)
	v_add_f32_e32 v30, v30, v31
	v_mov_b32_e32 v31, v30
	s_nop 1
	v_permlane32_swap_b32_e32 v30, v31
	v_add_f32_e32 v30, v30, v31
	v_fmamk_f32 v30, v30, 0x3a800000, v46
	v_mul_f32_e32 v31, 0x4b800000, v30
	v_cmp_gt_f32_e32 vcc, s14, v30
	s_nop 1
	v_cndmask_b32_e32 v30, v30, v31, vcc
	v_rsq_f32_e32 v30, v30
	s_nop 0
	v_mul_f32_e32 v31, 0x45800000, v30
	v_cndmask_b32_e32 v60, v30, v31, vcc
	v_pk_mul_f32 v[30:31], v[36:37], v[60:61] op_sel_hi:[1,0]
	v_pk_mul_f32 v[32:33], v[48:49], v[60:61] op_sel_hi:[1,0]
	v_pk_mul_f32 v[30:31], v[2:3], v[30:31]
	v_pk_mul_f32 v[36:37], v[0:1], v[32:33]
	v_cndmask_b32_e64 v33, v47, v31, s[0:1]
	v_cndmask_b32_e64 v32, v47, v30, s[0:1]
	v_cndmask_b32_e64 v31, v47, v37, s[0:1]
	v_cndmask_b32_e64 v30, v47, v36, s[0:1]
	global_store_dwordx4 v[62:63], v[30:33], off nt
	s_waitcnt vmcnt(4)
	v_mov_b64_e32 v[36:37], v[44:45]
	v_pk_mul_f32 v[30:31], v[34:35], v[60:61] op_sel_hi:[1,0]
	v_pk_mul_f32 v[32:33], v[50:51], v[60:61] op_sel_hi:[1,0]
	v_pk_mul_f32 v[30:31], v[6:7], v[30:31]
	v_pk_mul_f32 v[34:35], v[4:5], v[32:33]
	v_cndmask_b32_e64 v33, v47, v31, s[0:1]
	v_cndmask_b32_e64 v32, v47, v30, s[0:1]
	v_cndmask_b32_e64 v31, v47, v35, s[0:1]
	v_cndmask_b32_e64 v30, v47, v34, s[0:1]
	global_store_dwordx4 v[62:63], v[30:33], off offset:1024 nt
	s_nop 1
	v_pk_mul_f32 v[30:31], v[54:55], v[60:61] op_sel_hi:[1,0]
	v_pk_mul_f32 v[32:33], v[52:53], v[60:61] op_sel_hi:[1,0]
	v_pk_mul_f32 v[30:31], v[10:11], v[30:31]
	v_pk_mul_f32 v[34:35], v[8:9], v[32:33]
	v_cndmask_b32_e64 v33, v47, v31, s[0:1]
	v_cndmask_b32_e64 v32, v47, v30, s[0:1]
	v_cndmask_b32_e64 v31, v47, v35, s[0:1]
	v_cndmask_b32_e64 v30, v47, v34, s[0:1]
	global_store_dwordx4 v[62:63], v[30:33], off offset:2048 nt
	s_nop 1
	v_pk_mul_f32 v[30:31], v[58:59], v[60:61] op_sel_hi:[1,0]
	v_pk_mul_f32 v[32:33], v[56:57], v[60:61] op_sel_hi:[1,0]
	v_pk_mul_f32 v[30:31], v[14:15], v[30:31]
	v_pk_mul_f32 v[34:35], v[12:13], v[32:33]
	v_cndmask_b32_e64 v33, v47, v31, s[0:1]
	v_cndmask_b32_e64 v32, v47, v30, s[0:1]
	v_cndmask_b32_e64 v31, v47, v35, s[0:1]
	v_cndmask_b32_e64 v30, v47, v34, s[0:1]
	global_store_dwordx4 v[62:63], v[30:33], off offset:3072 nt
	s_waitcnt vmcnt(6)
	v_mov_b64_e32 v[34:35], v[42:43]
	s_waitcnt vmcnt(5)
	v_mov_b64_e32 v[32:33], v[40:41]
	s_waitcnt vmcnt(4)
	v_mov_b64_e32 v[30:31], v[38:39]

.LBB0_2588:
	v_lshlrev_b32_e32 v48, 16, v44
	v_and_b32_e32 v49, 0xffff0000, v44
	v_lshlrev_b32_e32 v44, 16, v45
	v_and_b32_e32 v45, 0xffff0000, v45
	v_mul_f32_e32 v50, v49, v49
	v_mul_f32_e32 v51, v45, v45
	v_fmac_f32_e32 v50, v48, v48
	v_fmac_f32_e32 v51, v44, v44
	v_add_f32_e32 v52, v50, v51
	v_lshlrev_b32_e32 v50, 16, v42
	v_and_b32_e32 v51, 0xffff0000, v42
	v_lshlrev_b32_e32 v42, 16, v43
	v_and_b32_e32 v43, 0xffff0000, v43
	v_mul_f32_e32 v53, v51, v51
	v_mul_f32_e32 v54, v43, v43
	v_fmac_f32_e32 v53, v50, v50
	v_fmac_f32_e32 v54, v42, v42
	v_add_f32_e32 v53, v53, v54
	v_add_f32_e32 v56, v52, v53
	v_and_b32_e32 v53, 0xffff0000, v40
	v_and_b32_e32 v55, 0xffff0000, v41
	v_lshlrev_b32_e32 v52, 16, v40
	v_lshlrev_b32_e32 v54, 16, v41
	v_mul_f32_e32 v40, v53, v53
	v_mul_f32_e32 v41, v55, v55
	v_fmac_f32_e32 v40, v52, v52
	v_fmac_f32_e32 v41, v54, v54
	v_add_f32_e32 v40, v40, v41
	v_and_b32_e32 v57, 0xffff0000, v38
	v_and_b32_e32 v59, 0xffff0000, v39
	v_add_f32_e32 v40, v56, v40
	v_lshlrev_b32_e32 v56, 16, v38
	v_lshlrev_b32_e32 v58, 16, v39
	v_mul_f32_e32 v38, v57, v57
	v_mul_f32_e32 v39, v59, v59
	v_fmac_f32_e32 v38, v56, v56
	v_fmac_f32_e32 v39, v58, v58
	v_add_f32_e32 v38, v38, v39
	v_add_f32_e32 v38, v40, v38
	ds_swizzle_b32 v39, v38 offset:swizzle(SWAP,1)
	s_cmpk_gt_i32 s4, 0x3fff
	s_mov_b64 s[12:13], -1
	s_waitcnt lgkmcnt(0)
	v_add_f32_e32 v38, v38, v39
	ds_swizzle_b32 v39, v38 offset:swizzle(SWAP,2)
	s_waitcnt lgkmcnt(0)
	v_add_f32_e32 v38, v38, v39
	ds_swizzle_b32 v39, v38 offset:swizzle(SWAP,4)
	s_waitcnt lgkmcnt(0)
	v_add_f32_e32 v38, v38, v39
	ds_swizzle_b32 v39, v38 offset:swizzle(SWAP,8)
	s_waitcnt lgkmcnt(0)
	v_add_f32_e32 v38, v38, v39
	ds_swizzle_b32 v39, v38 offset:swizzle(SWAP,16)
	s_waitcnt lgkmcnt(0)
	v_add_f32_e32 v38, v38, v39
	v_mov_b32_e32 v39, v38
	s_nop 1
	v_permlane32_swap_b32_e32 v38, v39
	v_add_f32_e32 v38, v38, v39
	v_fmamk_f32 v38, v38, 0x3a800000, v46
	v_mul_f32_e32 v39, 0x4b800000, v38
	v_cmp_gt_f32_e32 vcc, s14, v38
	s_nop 1
	v_cndmask_b32_e32 v38, v38, v39, vcc
	v_rsq_f32_e32 v38, v38
	s_nop 0
	v_mul_f32_e32 v39, 0x45800000, v38
	v_cndmask_b32_e32 v60, v38, v39, vcc
	v_pk_mul_f32 v[38:39], v[44:45], v[60:61] op_sel_hi:[1,0]
	v_pk_mul_f32 v[40:41], v[48:49], v[60:61] op_sel_hi:[1,0]
	v_pk_mul_f32 v[38:39], v[2:3], v[38:39]
	v_pk_mul_f32 v[44:45], v[0:1], v[40:41]
	v_cndmask_b32_e64 v41, v47, v39, s[0:1]
	v_cndmask_b32_e64 v40, v47, v38, s[0:1]
	v_cndmask_b32_e64 v39, v47, v45, s[0:1]
	v_cndmask_b32_e64 v38, v47, v44, s[0:1]
	global_store_dwordx4 v[20:21], v[38:41], off offset:-2048 nt
	s_nop 1
	v_pk_mul_f32 v[38:39], v[42:43], v[60:61] op_sel_hi:[1,0]
	v_pk_mul_f32 v[40:41], v[50:51], v[60:61] op_sel_hi:[1,0]
	v_pk_mul_f32 v[38:39], v[6:7], v[38:39]
	v_pk_mul_f32 v[42:43], v[4:5], v[40:41]
	v_cndmask_b32_e64 v41, v47, v39, s[0:1]
	v_cndmask_b32_e64 v40, v47, v38, s[0:1]
	v_cndmask_b32_e64 v39, v47, v43, s[0:1]
	v_cndmask_b32_e64 v38, v47, v42, s[0:1]
	global_store_dwordx4 v[20:21], v[38:41], off offset:-1024 nt
	s_nop 1
	v_pk_mul_f32 v[38:39], v[54:55], v[60:61] op_sel_hi:[1,0]
	v_pk_mul_f32 v[40:41], v[52:53], v[60:61] op_sel_hi:[1,0]
	v_pk_mul_f32 v[38:39], v[10:11], v[38:39]
	v_pk_mul_f32 v[42:43], v[8:9], v[40:41]
	v_cndmask_b32_e64 v41, v47, v39, s[0:1]
	v_cndmask_b32_e64 v40, v47, v38, s[0:1]
	v_cndmask_b32_e64 v39, v47, v43, s[0:1]
	v_cndmask_b32_e64 v38, v47, v42, s[0:1]
	global_store_dwordx4 v[20:21], v[38:41], off nt
	s_nop 1
	v_pk_mul_f32 v[38:39], v[58:59], v[60:61] op_sel_hi:[1,0]
	v_pk_mul_f32 v[40:41], v[56:57], v[60:61] op_sel_hi:[1,0]
	v_pk_mul_f32 v[38:39], v[14:15], v[38:39]
	v_pk_mul_f32 v[42:43], v[12:13], v[40:41]
	v_cndmask_b32_e64 v41, v47, v39, s[0:1]
	v_cndmask_b32_e64 v40, v47, v38, s[0:1]
	v_cndmask_b32_e64 v39, v47, v43, s[0:1]
	v_cndmask_b32_e64 v38, v47, v42, s[0:1]
	global_store_dwordx4 v[20:21], v[38:41], off offset:1024 nt
	s_cbranch_scc1 .LBB0_2585
	s_add_i32 s10, s15, s10
	s_cmpk_gt_i32 s10, 0x3fff
	v_mov_b64_e32 v[38:39], v[30:31]
	v_mov_b64_e32 v[40:41], v[32:33]
	v_mov_b64_e32 v[42:43], v[34:35]
	v_mov_b64_e32 v[44:45], v[36:37]
	s_cbranch_scc1 .LBB0_2584
	s_ashr_i32 s11, s10, 31
	s_lshl_b64 s[10:11], s[10:11], 12
	v_lshl_add_u64 v[48:49], v[16:17], 0, s[10:11]
	global_load_dwordx2 v[44:45], v[48:49], off
	global_load_dwordx2 v[42:43], v[48:49], off offset:512
	global_load_dwordx2 v[40:41], v[48:49], off offset:1024
	global_load_dwordx2 v[38:39], v[48:49], off offset:1536
	s_branch .LBB0_2584
